# phase-0 row RMSNorm hand-written: next trip prefetched into a second bank, DPP + batched bpermute reductions, scalar-base addressing, cvt_pk packing
# baseline (speedup 1.0000x reference)
.LBB0_444:
	s_mov_b64 s[0:1], exec
	v_readlane_b32 s56, v252, 10
	v_readlane_b32 s57, v252, 11
	v_readlane_b32 s58, v252, 12
	v_readlane_b32 s59, v252, 13
	v_readlane_b32 s60, v252, 14
	v_readlane_b32 s61, v252, 15
	v_readlane_b32 s62, v255, 10
	v_readlane_b32 s63, v255, 11
	v_readlane_b32 s64, v255, 6
	v_readlane_b32 s65, v255, 7
	v_readlane_b32 s66, v255, 8
	v_readlane_b32 s67, v255, 9
	v_readlane_b32 s68, v255, 14
	v_readlane_b32 s69, v255, 15
	v_readlane_b32 s70, v255, 12
	v_readlane_b32 s71, v255, 13
	v_readlane_b32 s2, v254, 13
	v_readlane_b32 s3, v254, 14
	v_readlane_b32 s20, v253, 28
	s_load_dword s43, s[74:75], 0x0
	v_lshrrev_b32_e32 v145, 6, v179
	v_and_b32_e32 v144, 63, v179
	v_xor_b32_e32 v160, 16, v225
	v_readfirstlane_b32 s21, v145
	v_xor_b32_e32 v161, 32, v225
	v_lshlrev_b32_e32 v145, 3, v144
	v_lshlrev_b32_e32 v144, 4, v144
	v_lshlrev_b32_e32 v160, 2, v160
	v_lshlrev_b32_e32 v161, 2, v161
	v_mov_b32_e32 v174, 0x3727c5ac
	s_lshl_b32 s21, s21, 2
	s_add_i32 s41, s20, s21
	s_mov_b32 s6, 0x3a800000
	s_cmp_lt_i32 s41, 0x8000
	s_cbranch_scc0 .Lrn_done
	global_load_dwordx4 v[0:3], v144, s[58:59]
	global_load_dwordx4 v[4:7], v144, s[58:59] offset:1024
	global_load_dwordx4 v[8:11], v144, s[58:59] offset:2048
	global_load_dwordx4 v[12:15], v144, s[58:59] offset:3072
	s_lshl_b32 s7, s41, 12
	v_add_u32_e32 v146, s7, v144
	v_add_u32_e32 v147, 0x1000, v146
	v_add_u32_e32 v148, 0x2000, v146
	v_add_u32_e32 v149, 0x3000, v146
	global_load_dwordx4 v[16:19], v146, s[56:57] nt
	global_load_dwordx4 v[20:23], v146, s[56:57] offset:1024 nt
	global_load_dwordx4 v[24:27], v146, s[56:57] offset:2048 nt
	global_load_dwordx4 v[28:31], v146, s[56:57] offset:3072 nt
	global_load_dwordx4 v[32:35], v147, s[56:57] nt
	global_load_dwordx4 v[36:39], v147, s[56:57] offset:1024 nt
	global_load_dwordx4 v[40:43], v147, s[56:57] offset:2048 nt
	global_load_dwordx4 v[44:47], v147, s[56:57] offset:3072 nt
	global_load_dwordx4 v[48:51], v148, s[56:57] nt
	global_load_dwordx4 v[52:55], v148, s[56:57] offset:1024 nt
	global_load_dwordx4 v[56:59], v148, s[56:57] offset:2048 nt
	global_load_dwordx4 v[60:63], v148, s[56:57] offset:3072 nt
	global_load_dwordx4 v[64:67], v149, s[56:57] nt
	global_load_dwordx4 v[68:71], v149, s[56:57] offset:1024 nt
	global_load_dwordx4 v[72:75], v149, s[56:57] offset:2048 nt
	global_load_dwordx4 v[76:79], v149, s[56:57] offset:3072 nt
	s_waitcnt lgkmcnt(0)
	s_lshl_b32 s43, s43, 5
	s_add_i32 s39, s41, s43
	s_cmp_lt_i32 s39, 0x8000
	s_cbranch_scc0 .Lrn_first_nol
	s_lshl_b32 s7, s39, 12
	v_add_u32_e32 v146, s7, v144
	v_add_u32_e32 v147, 0x1000, v146
	v_add_u32_e32 v148, 0x2000, v146
	v_add_u32_e32 v149, 0x3000, v146
	global_load_dwordx4 v[80:83], v146, s[56:57] nt
	global_load_dwordx4 v[84:87], v146, s[56:57] offset:1024 nt
	global_load_dwordx4 v[88:91], v146, s[56:57] offset:2048 nt
	global_load_dwordx4 v[92:95], v146, s[56:57] offset:3072 nt
	global_load_dwordx4 v[96:99], v147, s[56:57] nt
	global_load_dwordx4 v[100:103], v147, s[56:57] offset:1024 nt
	global_load_dwordx4 v[104:107], v147, s[56:57] offset:2048 nt
	global_load_dwordx4 v[108:111], v147, s[56:57] offset:3072 nt
	global_load_dwordx4 v[112:115], v148, s[56:57] nt
	global_load_dwordx4 v[116:119], v148, s[56:57] offset:1024 nt
	global_load_dwordx4 v[120:123], v148, s[56:57] offset:2048 nt
	global_load_dwordx4 v[124:127], v148, s[56:57] offset:3072 nt
	global_load_dwordx4 v[128:131], v149, s[56:57] nt
	global_load_dwordx4 v[132:135], v149, s[56:57] offset:1024 nt
	global_load_dwordx4 v[136:139], v149, s[56:57] offset:2048 nt
	global_load_dwordx4 v[140:143], v149, s[56:57] offset:3072 nt
	s_waitcnt vmcnt(16)
	s_branch .Lrn_comp_A

.Lrn_step_A:
	s_add_i32 s39, s41, s43
	s_cmp_lt_i32 s39, 0x8000
	s_cbranch_scc0 .Lrn_nol_A
	s_lshl_b32 s7, s39, 12
	v_add_u32_e32 v146, s7, v144
	v_add_u32_e32 v147, 0x1000, v146
	v_add_u32_e32 v148, 0x2000, v146
	v_add_u32_e32 v149, 0x3000, v146
	global_load_dwordx4 v[80:83], v146, s[56:57] nt
	global_load_dwordx4 v[84:87], v146, s[56:57] offset:1024 nt
	global_load_dwordx4 v[88:91], v146, s[56:57] offset:2048 nt
	global_load_dwordx4 v[92:95], v146, s[56:57] offset:3072 nt
	global_load_dwordx4 v[96:99], v147, s[56:57] nt
	global_load_dwordx4 v[100:103], v147, s[56:57] offset:1024 nt
	global_load_dwordx4 v[104:107], v147, s[56:57] offset:2048 nt
	global_load_dwordx4 v[108:111], v147, s[56:57] offset:3072 nt
	global_load_dwordx4 v[112:115], v148, s[56:57] nt
	global_load_dwordx4 v[116:119], v148, s[56:57] offset:1024 nt
	global_load_dwordx4 v[120:123], v148, s[56:57] offset:2048 nt
	global_load_dwordx4 v[124:127], v148, s[56:57] offset:3072 nt
	global_load_dwordx4 v[128:131], v149, s[56:57] nt
	global_load_dwordx4 v[132:135], v149, s[56:57] offset:1024 nt
	global_load_dwordx4 v[136:139], v149, s[56:57] offset:2048 nt
	global_load_dwordx4 v[140:143], v149, s[56:57] offset:3072 nt
	s_waitcnt vmcnt(32)
	s_branch .Lrn_comp_A

.Lrn_comp_A:
	v_pk_mul_f32 v[164:165], v[16:17], v[16:17]
	v_pk_mul_f32 v[166:167], v[32:33], v[32:33]
	v_pk_mul_f32 v[168:169], v[48:49], v[48:49]
	v_pk_mul_f32 v[170:171], v[64:65], v[64:65]
	v_pk_fma_f32 v[164:165], v[18:19], v[18:19], v[164:165]
	v_pk_fma_f32 v[166:167], v[34:35], v[34:35], v[166:167]
	v_pk_fma_f32 v[168:169], v[50:51], v[50:51], v[168:169]
	v_pk_fma_f32 v[170:171], v[66:67], v[66:67], v[170:171]
	v_pk_fma_f32 v[164:165], v[20:21], v[20:21], v[164:165]
	v_pk_fma_f32 v[166:167], v[36:37], v[36:37], v[166:167]
	v_pk_fma_f32 v[168:169], v[52:53], v[52:53], v[168:169]
	v_pk_fma_f32 v[170:171], v[68:69], v[68:69], v[170:171]
	v_pk_fma_f32 v[164:165], v[22:23], v[22:23], v[164:165]
	v_pk_fma_f32 v[166:167], v[38:39], v[38:39], v[166:167]
	v_pk_fma_f32 v[168:169], v[54:55], v[54:55], v[168:169]
	v_pk_fma_f32 v[170:171], v[70:71], v[70:71], v[170:171]
	v_pk_fma_f32 v[164:165], v[24:25], v[24:25], v[164:165]
	v_pk_fma_f32 v[166:167], v[40:41], v[40:41], v[166:167]
	v_pk_fma_f32 v[168:169], v[56:57], v[56:57], v[168:169]
	v_pk_fma_f32 v[170:171], v[72:73], v[72:73], v[170:171]
	v_pk_fma_f32 v[164:165], v[26:27], v[26:27], v[164:165]
	v_pk_fma_f32 v[166:167], v[42:43], v[42:43], v[166:167]
	v_pk_fma_f32 v[168:169], v[58:59], v[58:59], v[168:169]
	v_pk_fma_f32 v[170:171], v[74:75], v[74:75], v[170:171]
	v_pk_fma_f32 v[164:165], v[28:29], v[28:29], v[164:165]
	v_pk_fma_f32 v[166:167], v[44:45], v[44:45], v[166:167]
	v_pk_fma_f32 v[168:169], v[60:61], v[60:61], v[168:169]
	v_pk_fma_f32 v[170:171], v[76:77], v[76:77], v[170:171]
	v_pk_fma_f32 v[164:165], v[30:31], v[30:31], v[164:165]
	v_pk_fma_f32 v[166:167], v[46:47], v[46:47], v[166:167]
	v_pk_fma_f32 v[168:169], v[62:63], v[62:63], v[168:169]
	v_pk_fma_f32 v[170:171], v[78:79], v[78:79], v[170:171]
	v_add_f32_e32 v152, v164, v165
	v_add_f32_e32 v153, v166, v167
	v_add_f32_e32 v154, v168, v169
	v_add_f32_e32 v155, v170, v171
	s_lshl_b32 s7, s41, 11
	v_add_u32_e32 v150, s7, v145
	v_add_f32_dpp v156, v152, v152 quad_perm:[1,0,3,2] row_mask:0xf bank_mask:0xf
	v_add_f32_dpp v157, v153, v153 quad_perm:[1,0,3,2] row_mask:0xf bank_mask:0xf
	v_add_f32_dpp v158, v154, v154 quad_perm:[1,0,3,2] row_mask:0xf bank_mask:0xf
	v_add_f32_dpp v159, v155, v155 quad_perm:[1,0,3,2] row_mask:0xf bank_mask:0xf
	v_add_u32_e32 v151, 0x1000, v150
	v_add_f32_dpp v152, v156, v156 quad_perm:[2,3,0,1] row_mask:0xf bank_mask:0xf
	v_add_f32_dpp v153, v157, v157 quad_perm:[2,3,0,1] row_mask:0xf bank_mask:0xf
	v_add_f32_dpp v154, v158, v158 quad_perm:[2,3,0,1] row_mask:0xf bank_mask:0xf
	v_add_f32_dpp v155, v159, v159 quad_perm:[2,3,0,1] row_mask:0xf bank_mask:0xf
	s_nop 0
	v_add_f32_dpp v156, v152, v152 row_ror:4 row_mask:0xf bank_mask:0xf
	v_add_f32_dpp v157, v153, v153 row_ror:4 row_mask:0xf bank_mask:0xf
	v_add_f32_dpp v158, v154, v154 row_ror:4 row_mask:0xf bank_mask:0xf
	v_add_f32_dpp v159, v155, v155 row_ror:4 row_mask:0xf bank_mask:0xf
	s_nop 0
	v_add_f32_dpp v152, v156, v156 row_ror:8 row_mask:0xf bank_mask:0xf
	v_add_f32_dpp v153, v157, v157 row_ror:8 row_mask:0xf bank_mask:0xf
	v_add_f32_dpp v154, v158, v158 row_ror:8 row_mask:0xf bank_mask:0xf
	v_add_f32_dpp v155, v159, v159 row_ror:8 row_mask:0xf bank_mask:0xf
	ds_bpermute_b32 v156, v160, v152
	ds_bpermute_b32 v157, v160, v153
	ds_bpermute_b32 v158, v160, v154
	ds_bpermute_b32 v159, v160, v155
	s_waitcnt lgkmcnt(0)
	v_add_f32_e32 v152, v152, v156
	v_add_f32_e32 v153, v153, v157
	v_add_f32_e32 v154, v154, v158
	v_add_f32_e32 v155, v155, v159
	ds_bpermute_b32 v156, v161, v152
	ds_bpermute_b32 v157, v161, v153
	ds_bpermute_b32 v158, v161, v154
	ds_bpermute_b32 v159, v161, v155
	s_waitcnt lgkmcnt(0)
	v_add_f32_e32 v152, v152, v156
	v_add_f32_e32 v153, v153, v157
	v_add_f32_e32 v154, v154, v158
	v_add_f32_e32 v155, v155, v159
	v_fma_f32 v152, v152, s6, v174
	v_fma_f32 v153, v153, s6, v174
	v_fma_f32 v154, v154, s6, v174
	v_fma_f32 v155, v155, s6, v174
	v_rsq_f32_e32 v164, v152
	v_rsq_f32_e32 v166, v153
	v_rsq_f32_e32 v168, v154
	v_rsq_f32_e32 v170, v155
	v_pk_mul_f32 v[16:17], v[16:17], v[164:165] op_sel_hi:[1,0]
	v_pk_mul_f32 v[18:19], v[18:19], v[164:165] op_sel_hi:[1,0]
	v_pk_mul_f32 v[16:17], v[0:1], v[16:17]
	v_pk_mul_f32 v[18:19], v[2:3], v[18:19]
	v_cvt_pk_bf16_f32 v16, v16, v17
	v_cvt_pk_bf16_f32 v17, v18, v19
	global_store_dwordx2 v150, v[16:17], s[2:3] sc1
	v_pk_mul_f32 v[20:21], v[20:21], v[164:165] op_sel_hi:[1,0]
	v_pk_mul_f32 v[22:23], v[22:23], v[164:165] op_sel_hi:[1,0]
	v_pk_mul_f32 v[20:21], v[4:5], v[20:21]
	v_pk_mul_f32 v[22:23], v[6:7], v[22:23]
	v_cvt_pk_bf16_f32 v20, v20, v21
	v_cvt_pk_bf16_f32 v21, v22, v23
	global_store_dwordx2 v150, v[20:21], s[2:3] offset:512 sc1
	v_pk_mul_f32 v[24:25], v[24:25], v[164:165] op_sel_hi:[1,0]
	v_pk_mul_f32 v[26:27], v[26:27], v[164:165] op_sel_hi:[1,0]
	v_pk_mul_f32 v[24:25], v[8:9], v[24:25]
	v_pk_mul_f32 v[26:27], v[10:11], v[26:27]
	v_cvt_pk_bf16_f32 v24, v24, v25
	v_cvt_pk_bf16_f32 v25, v26, v27
	global_store_dwordx2 v150, v[24:25], s[2:3] offset:1024 sc1
	v_pk_mul_f32 v[28:29], v[28:29], v[164:165] op_sel_hi:[1,0]
	v_pk_mul_f32 v[30:31], v[30:31], v[164:165] op_sel_hi:[1,0]
	v_pk_mul_f32 v[28:29], v[12:13], v[28:29]
	v_pk_mul_f32 v[30:31], v[14:15], v[30:31]
	v_cvt_pk_bf16_f32 v28, v28, v29
	v_cvt_pk_bf16_f32 v29, v30, v31
	global_store_dwordx2 v150, v[28:29], s[2:3] offset:1536 sc1
	v_pk_mul_f32 v[32:33], v[32:33], v[166:167] op_sel_hi:[1,0]
	v_pk_mul_f32 v[34:35], v[34:35], v[166:167] op_sel_hi:[1,0]
	v_pk_mul_f32 v[32:33], v[0:1], v[32:33]
	v_pk_mul_f32 v[34:35], v[2:3], v[34:35]
	v_cvt_pk_bf16_f32 v32, v32, v33
	v_cvt_pk_bf16_f32 v33, v34, v35
	global_store_dwordx2 v150, v[32:33], s[2:3] offset:2048 sc1
	v_pk_mul_f32 v[36:37], v[36:37], v[166:167] op_sel_hi:[1,0]
	v_pk_mul_f32 v[38:39], v[38:39], v[166:167] op_sel_hi:[1,0]
	v_pk_mul_f32 v[36:37], v[4:5], v[36:37]
	v_pk_mul_f32 v[38:39], v[6:7], v[38:39]
	v_cvt_pk_bf16_f32 v36, v36, v37
	v_cvt_pk_bf16_f32 v37, v38, v39
	global_store_dwordx2 v150, v[36:37], s[2:3] offset:2560 sc1
	v_pk_mul_f32 v[40:41], v[40:41], v[166:167] op_sel_hi:[1,0]
	v_pk_mul_f32 v[42:43], v[42:43], v[166:167] op_sel_hi:[1,0]
	v_pk_mul_f32 v[40:41], v[8:9], v[40:41]
	v_pk_mul_f32 v[42:43], v[10:11], v[42:43]
	v_cvt_pk_bf16_f32 v40, v40, v41
	v_cvt_pk_bf16_f32 v41, v42, v43
	global_store_dwordx2 v150, v[40:41], s[2:3] offset:3072 sc1
	v_pk_mul_f32 v[44:45], v[44:45], v[166:167] op_sel_hi:[1,0]
	v_pk_mul_f32 v[46:47], v[46:47], v[166:167] op_sel_hi:[1,0]
	v_pk_mul_f32 v[44:45], v[12:13], v[44:45]
	v_pk_mul_f32 v[46:47], v[14:15], v[46:47]
	v_cvt_pk_bf16_f32 v44, v44, v45
	v_cvt_pk_bf16_f32 v45, v46, v47
	global_store_dwordx2 v150, v[44:45], s[2:3] offset:3584 sc1
	v_pk_mul_f32 v[48:49], v[48:49], v[168:169] op_sel_hi:[1,0]
	v_pk_mul_f32 v[50:51], v[50:51], v[168:169] op_sel_hi:[1,0]
	v_pk_mul_f32 v[48:49], v[0:1], v[48:49]
	v_pk_mul_f32 v[50:51], v[2:3], v[50:51]
	v_cvt_pk_bf16_f32 v48, v48, v49
	v_cvt_pk_bf16_f32 v49, v50, v51
	global_store_dwordx2 v151, v[48:49], s[2:3] sc1
	v_pk_mul_f32 v[52:53], v[52:53], v[168:169] op_sel_hi:[1,0]
	v_pk_mul_f32 v[54:55], v[54:55], v[168:169] op_sel_hi:[1,0]
	v_pk_mul_f32 v[52:53], v[4:5], v[52:53]
	v_pk_mul_f32 v[54:55], v[6:7], v[54:55]
	v_cvt_pk_bf16_f32 v52, v52, v53
	v_cvt_pk_bf16_f32 v53, v54, v55
	global_store_dwordx2 v151, v[52:53], s[2:3] offset:512 sc1
	v_pk_mul_f32 v[56:57], v[56:57], v[168:169] op_sel_hi:[1,0]
	v_pk_mul_f32 v[58:59], v[58:59], v[168:169] op_sel_hi:[1,0]
	v_pk_mul_f32 v[56:57], v[8:9], v[56:57]
	v_pk_mul_f32 v[58:59], v[10:11], v[58:59]
	v_cvt_pk_bf16_f32 v56, v56, v57
	v_cvt_pk_bf16_f32 v57, v58, v59
	global_store_dwordx2 v151, v[56:57], s[2:3] offset:1024 sc1
	v_pk_mul_f32 v[60:61], v[60:61], v[168:169] op_sel_hi:[1,0]
	v_pk_mul_f32 v[62:63], v[62:63], v[168:169] op_sel_hi:[1,0]
	v_pk_mul_f32 v[60:61], v[12:13], v[60:61]
	v_pk_mul_f32 v[62:63], v[14:15], v[62:63]
	v_cvt_pk_bf16_f32 v60, v60, v61
	v_cvt_pk_bf16_f32 v61, v62, v63
	global_store_dwordx2 v151, v[60:61], s[2:3] offset:1536 sc1
	v_pk_mul_f32 v[64:65], v[64:65], v[170:171] op_sel_hi:[1,0]
	v_pk_mul_f32 v[66:67], v[66:67], v[170:171] op_sel_hi:[1,0]
	v_pk_mul_f32 v[64:65], v[0:1], v[64:65]
	v_pk_mul_f32 v[66:67], v[2:3], v[66:67]
	v_cvt_pk_bf16_f32 v64, v64, v65
	v_cvt_pk_bf16_f32 v65, v66, v67
	global_store_dwordx2 v151, v[64:65], s[2:3] offset:2048 sc1
	v_pk_mul_f32 v[68:69], v[68:69], v[170:171] op_sel_hi:[1,0]
	v_pk_mul_f32 v[70:71], v[70:71], v[170:171] op_sel_hi:[1,0]
	v_pk_mul_f32 v[68:69], v[4:5], v[68:69]
	v_pk_mul_f32 v[70:71], v[6:7], v[70:71]
	v_cvt_pk_bf16_f32 v68, v68, v69
	v_cvt_pk_bf16_f32 v69, v70, v71
	global_store_dwordx2 v151, v[68:69], s[2:3] offset:2560 sc1
	v_pk_mul_f32 v[72:73], v[72:73], v[170:171] op_sel_hi:[1,0]
	v_pk_mul_f32 v[74:75], v[74:75], v[170:171] op_sel_hi:[1,0]
	v_pk_mul_f32 v[72:73], v[8:9], v[72:73]
	v_pk_mul_f32 v[74:75], v[10:11], v[74:75]
	v_cvt_pk_bf16_f32 v72, v72, v73
	v_cvt_pk_bf16_f32 v73, v74, v75
	global_store_dwordx2 v151, v[72:73], s[2:3] offset:3072 sc1
	v_pk_mul_f32 v[76:77], v[76:77], v[170:171] op_sel_hi:[1,0]
	v_pk_mul_f32 v[78:79], v[78:79], v[170:171] op_sel_hi:[1,0]
	v_pk_mul_f32 v[76:77], v[12:13], v[76:77]
	v_pk_mul_f32 v[78:79], v[14:15], v[78:79]
	v_cvt_pk_bf16_f32 v76, v76, v77
	v_cvt_pk_bf16_f32 v77, v78, v79
	global_store_dwordx2 v151, v[76:77], s[2:3] offset:3584 sc1
	s_mov_b32 s41, s39
	s_cmp_lt_i32 s41, 0x8000
	s_cbranch_scc0 .Lrn_done
.Lrn_step_B:
	s_add_i32 s39, s41, s43
	s_cmp_lt_i32 s39, 0x8000
	s_cbranch_scc0 .Lrn_nol_B
	s_lshl_b32 s7, s39, 12
	v_add_u32_e32 v146, s7, v144
	v_add_u32_e32 v147, 0x1000, v146
	v_add_u32_e32 v148, 0x2000, v146
	v_add_u32_e32 v149, 0x3000, v146
	global_load_dwordx4 v[16:19], v146, s[56:57] nt
	global_load_dwordx4 v[20:23], v146, s[56:57] offset:1024 nt
	global_load_dwordx4 v[24:27], v146, s[56:57] offset:2048 nt
	global_load_dwordx4 v[28:31], v146, s[56:57] offset:3072 nt
	global_load_dwordx4 v[32:35], v147, s[56:57] nt
	global_load_dwordx4 v[36:39], v147, s[56:57] offset:1024 nt
	global_load_dwordx4 v[40:43], v147, s[56:57] offset:2048 nt
	global_load_dwordx4 v[44:47], v147, s[56:57] offset:3072 nt
	global_load_dwordx4 v[48:51], v148, s[56:57] nt
	global_load_dwordx4 v[52:55], v148, s[56:57] offset:1024 nt
	global_load_dwordx4 v[56:59], v148, s[56:57] offset:2048 nt
	global_load_dwordx4 v[60:63], v148, s[56:57] offset:3072 nt
	global_load_dwordx4 v[64:67], v149, s[56:57] nt
	global_load_dwordx4 v[68:71], v149, s[56:57] offset:1024 nt
	global_load_dwordx4 v[72:75], v149, s[56:57] offset:2048 nt
	global_load_dwordx4 v[76:79], v149, s[56:57] offset:3072 nt
	s_waitcnt vmcnt(32)
	s_branch .Lrn_comp_B

.Lrn_comp_B:
	v_pk_mul_f32 v[164:165], v[80:81], v[80:81]
	v_pk_mul_f32 v[166:167], v[96:97], v[96:97]
	v_pk_mul_f32 v[168:169], v[112:113], v[112:113]
	v_pk_mul_f32 v[170:171], v[128:129], v[128:129]
	v_pk_fma_f32 v[164:165], v[82:83], v[82:83], v[164:165]
	v_pk_fma_f32 v[166:167], v[98:99], v[98:99], v[166:167]
	v_pk_fma_f32 v[168:169], v[114:115], v[114:115], v[168:169]
	v_pk_fma_f32 v[170:171], v[130:131], v[130:131], v[170:171]
	v_pk_fma_f32 v[164:165], v[84:85], v[84:85], v[164:165]
	v_pk_fma_f32 v[166:167], v[100:101], v[100:101], v[166:167]
	v_pk_fma_f32 v[168:169], v[116:117], v[116:117], v[168:169]
	v_pk_fma_f32 v[170:171], v[132:133], v[132:133], v[170:171]
	v_pk_fma_f32 v[164:165], v[86:87], v[86:87], v[164:165]
	v_pk_fma_f32 v[166:167], v[102:103], v[102:103], v[166:167]
	v_pk_fma_f32 v[168:169], v[118:119], v[118:119], v[168:169]
	v_pk_fma_f32 v[170:171], v[134:135], v[134:135], v[170:171]
	v_pk_fma_f32 v[164:165], v[88:89], v[88:89], v[164:165]
	v_pk_fma_f32 v[166:167], v[104:105], v[104:105], v[166:167]
	v_pk_fma_f32 v[168:169], v[120:121], v[120:121], v[168:169]
	v_pk_fma_f32 v[170:171], v[136:137], v[136:137], v[170:171]
	v_pk_fma_f32 v[164:165], v[90:91], v[90:91], v[164:165]
	v_pk_fma_f32 v[166:167], v[106:107], v[106:107], v[166:167]
	v_pk_fma_f32 v[168:169], v[122:123], v[122:123], v[168:169]
	v_pk_fma_f32 v[170:171], v[138:139], v[138:139], v[170:171]
	v_pk_fma_f32 v[164:165], v[92:93], v[92:93], v[164:165]
	v_pk_fma_f32 v[166:167], v[108:109], v[108:109], v[166:167]
	v_pk_fma_f32 v[168:169], v[124:125], v[124:125], v[168:169]
	v_pk_fma_f32 v[170:171], v[140:141], v[140:141], v[170:171]
	v_pk_fma_f32 v[164:165], v[94:95], v[94:95], v[164:165]
	v_pk_fma_f32 v[166:167], v[110:111], v[110:111], v[166:167]
	v_pk_fma_f32 v[168:169], v[126:127], v[126:127], v[168:169]
	v_pk_fma_f32 v[170:171], v[142:143], v[142:143], v[170:171]
	v_add_f32_e32 v152, v164, v165
	v_add_f32_e32 v153, v166, v167
	v_add_f32_e32 v154, v168, v169
	v_add_f32_e32 v155, v170, v171
	s_lshl_b32 s7, s41, 11
	v_add_u32_e32 v150, s7, v145
	v_add_f32_dpp v156, v152, v152 quad_perm:[1,0,3,2] row_mask:0xf bank_mask:0xf
	v_add_f32_dpp v157, v153, v153 quad_perm:[1,0,3,2] row_mask:0xf bank_mask:0xf
	v_add_f32_dpp v158, v154, v154 quad_perm:[1,0,3,2] row_mask:0xf bank_mask:0xf
	v_add_f32_dpp v159, v155, v155 quad_perm:[1,0,3,2] row_mask:0xf bank_mask:0xf
	v_add_u32_e32 v151, 0x1000, v150
	v_add_f32_dpp v152, v156, v156 quad_perm:[2,3,0,1] row_mask:0xf bank_mask:0xf
	v_add_f32_dpp v153, v157, v157 quad_perm:[2,3,0,1] row_mask:0xf bank_mask:0xf
	v_add_f32_dpp v154, v158, v158 quad_perm:[2,3,0,1] row_mask:0xf bank_mask:0xf
	v_add_f32_dpp v155, v159, v159 quad_perm:[2,3,0,1] row_mask:0xf bank_mask:0xf
	s_nop 0
	v_add_f32_dpp v156, v152, v152 row_ror:4 row_mask:0xf bank_mask:0xf
	v_add_f32_dpp v157, v153, v153 row_ror:4 row_mask:0xf bank_mask:0xf
	v_add_f32_dpp v158, v154, v154 row_ror:4 row_mask:0xf bank_mask:0xf
	v_add_f32_dpp v159, v155, v155 row_ror:4 row_mask:0xf bank_mask:0xf
	s_nop 0
	v_add_f32_dpp v152, v156, v156 row_ror:8 row_mask:0xf bank_mask:0xf
	v_add_f32_dpp v153, v157, v157 row_ror:8 row_mask:0xf bank_mask:0xf
	v_add_f32_dpp v154, v158, v158 row_ror:8 row_mask:0xf bank_mask:0xf
	v_add_f32_dpp v155, v159, v159 row_ror:8 row_mask:0xf bank_mask:0xf
	ds_bpermute_b32 v156, v160, v152
	ds_bpermute_b32 v157, v160, v153
	ds_bpermute_b32 v158, v160, v154
	ds_bpermute_b32 v159, v160, v155
	s_waitcnt lgkmcnt(0)
	v_add_f32_e32 v152, v152, v156
	v_add_f32_e32 v153, v153, v157
	v_add_f32_e32 v154, v154, v158
	v_add_f32_e32 v155, v155, v159
	ds_bpermute_b32 v156, v161, v152
	ds_bpermute_b32 v157, v161, v153
	ds_bpermute_b32 v158, v161, v154
	ds_bpermute_b32 v159, v161, v155
	s_waitcnt lgkmcnt(0)
	v_add_f32_e32 v152, v152, v156
	v_add_f32_e32 v153, v153, v157
	v_add_f32_e32 v154, v154, v158
	v_add_f32_e32 v155, v155, v159
	v_fma_f32 v152, v152, s6, v174
	v_fma_f32 v153, v153, s6, v174
	v_fma_f32 v154, v154, s6, v174
	v_fma_f32 v155, v155, s6, v174
	v_rsq_f32_e32 v164, v152
	v_rsq_f32_e32 v166, v153
	v_rsq_f32_e32 v168, v154
	v_rsq_f32_e32 v170, v155
	v_pk_mul_f32 v[80:81], v[80:81], v[164:165] op_sel_hi:[1,0]
	v_pk_mul_f32 v[82:83], v[82:83], v[164:165] op_sel_hi:[1,0]
	v_pk_mul_f32 v[80:81], v[0:1], v[80:81]
	v_pk_mul_f32 v[82:83], v[2:3], v[82:83]
	v_cvt_pk_bf16_f32 v80, v80, v81
	v_cvt_pk_bf16_f32 v81, v82, v83
	global_store_dwordx2 v150, v[80:81], s[2:3] sc1
	v_pk_mul_f32 v[84:85], v[84:85], v[164:165] op_sel_hi:[1,0]
	v_pk_mul_f32 v[86:87], v[86:87], v[164:165] op_sel_hi:[1,0]
	v_pk_mul_f32 v[84:85], v[4:5], v[84:85]
	v_pk_mul_f32 v[86:87], v[6:7], v[86:87]
	v_cvt_pk_bf16_f32 v84, v84, v85
	v_cvt_pk_bf16_f32 v85, v86, v87
	global_store_dwordx2 v150, v[84:85], s[2:3] offset:512 sc1
	v_pk_mul_f32 v[88:89], v[88:89], v[164:165] op_sel_hi:[1,0]
	v_pk_mul_f32 v[90:91], v[90:91], v[164:165] op_sel_hi:[1,0]
	v_pk_mul_f32 v[88:89], v[8:9], v[88:89]
	v_pk_mul_f32 v[90:91], v[10:11], v[90:91]
	v_cvt_pk_bf16_f32 v88, v88, v89
	v_cvt_pk_bf16_f32 v89, v90, v91
	global_store_dwordx2 v150, v[88:89], s[2:3] offset:1024 sc1
	v_pk_mul_f32 v[92:93], v[92:93], v[164:165] op_sel_hi:[1,0]
	v_pk_mul_f32 v[94:95], v[94:95], v[164:165] op_sel_hi:[1,0]
	v_pk_mul_f32 v[92:93], v[12:13], v[92:93]
	v_pk_mul_f32 v[94:95], v[14:15], v[94:95]
	v_cvt_pk_bf16_f32 v92, v92, v93
	v_cvt_pk_bf16_f32 v93, v94, v95
	global_store_dwordx2 v150, v[92:93], s[2:3] offset:1536 sc1
	v_pk_mul_f32 v[96:97], v[96:97], v[166:167] op_sel_hi:[1,0]
	v_pk_mul_f32 v[98:99], v[98:99], v[166:167] op_sel_hi:[1,0]
	v_pk_mul_f32 v[96:97], v[0:1], v[96:97]
	v_pk_mul_f32 v[98:99], v[2:3], v[98:99]
	v_cvt_pk_bf16_f32 v96, v96, v97
	v_cvt_pk_bf16_f32 v97, v98, v99
	global_store_dwordx2 v150, v[96:97], s[2:3] offset:2048 sc1
	v_pk_mul_f32 v[100:101], v[100:101], v[166:167] op_sel_hi:[1,0]
	v_pk_mul_f32 v[102:103], v[102:103], v[166:167] op_sel_hi:[1,0]
	v_pk_mul_f32 v[100:101], v[4:5], v[100:101]
	v_pk_mul_f32 v[102:103], v[6:7], v[102:103]
	v_cvt_pk_bf16_f32 v100, v100, v101
	v_cvt_pk_bf16_f32 v101, v102, v103
	global_store_dwordx2 v150, v[100:101], s[2:3] offset:2560 sc1
	v_pk_mul_f32 v[104:105], v[104:105], v[166:167] op_sel_hi:[1,0]
	v_pk_mul_f32 v[106:107], v[106:107], v[166:167] op_sel_hi:[1,0]
	v_pk_mul_f32 v[104:105], v[8:9], v[104:105]
	v_pk_mul_f32 v[106:107], v[10:11], v[106:107]
	v_cvt_pk_bf16_f32 v104, v104, v105
	v_cvt_pk_bf16_f32 v105, v106, v107
	global_store_dwordx2 v150, v[104:105], s[2:3] offset:3072 sc1
	v_pk_mul_f32 v[108:109], v[108:109], v[166:167] op_sel_hi:[1,0]
	v_pk_mul_f32 v[110:111], v[110:111], v[166:167] op_sel_hi:[1,0]
	v_pk_mul_f32 v[108:109], v[12:13], v[108:109]
	v_pk_mul_f32 v[110:111], v[14:15], v[110:111]
	v_cvt_pk_bf16_f32 v108, v108, v109
	v_cvt_pk_bf16_f32 v109, v110, v111
	global_store_dwordx2 v150, v[108:109], s[2:3] offset:3584 sc1
	v_pk_mul_f32 v[112:113], v[112:113], v[168:169] op_sel_hi:[1,0]
	v_pk_mul_f32 v[114:115], v[114:115], v[168:169] op_sel_hi:[1,0]
	v_pk_mul_f32 v[112:113], v[0:1], v[112:113]
	v_pk_mul_f32 v[114:115], v[2:3], v[114:115]
	v_cvt_pk_bf16_f32 v112, v112, v113
	v_cvt_pk_bf16_f32 v113, v114, v115
	global_store_dwordx2 v151, v[112:113], s[2:3] sc1
	v_pk_mul_f32 v[116:117], v[116:117], v[168:169] op_sel_hi:[1,0]
	v_pk_mul_f32 v[118:119], v[118:119], v[168:169] op_sel_hi:[1,0]
	v_pk_mul_f32 v[116:117], v[4:5], v[116:117]
	v_pk_mul_f32 v[118:119], v[6:7], v[118:119]
	v_cvt_pk_bf16_f32 v116, v116, v117
	v_cvt_pk_bf16_f32 v117, v118, v119
	global_store_dwordx2 v151, v[116:117], s[2:3] offset:512 sc1
	v_pk_mul_f32 v[120:121], v[120:121], v[168:169] op_sel_hi:[1,0]
	v_pk_mul_f32 v[122:123], v[122:123], v[168:169] op_sel_hi:[1,0]
	v_pk_mul_f32 v[120:121], v[8:9], v[120:121]
	v_pk_mul_f32 v[122:123], v[10:11], v[122:123]
	v_cvt_pk_bf16_f32 v120, v120, v121
	v_cvt_pk_bf16_f32 v121, v122, v123
	global_store_dwordx2 v151, v[120:121], s[2:3] offset:1024 sc1
	v_pk_mul_f32 v[124:125], v[124:125], v[168:169] op_sel_hi:[1,0]
	v_pk_mul_f32 v[126:127], v[126:127], v[168:169] op_sel_hi:[1,0]
	v_pk_mul_f32 v[124:125], v[12:13], v[124:125]
	v_pk_mul_f32 v[126:127], v[14:15], v[126:127]
	v_cvt_pk_bf16_f32 v124, v124, v125
	v_cvt_pk_bf16_f32 v125, v126, v127
	global_store_dwordx2 v151, v[124:125], s[2:3] offset:1536 sc1
	v_pk_mul_f32 v[128:129], v[128:129], v[170:171] op_sel_hi:[1,0]
	v_pk_mul_f32 v[130:131], v[130:131], v[170:171] op_sel_hi:[1,0]
	v_pk_mul_f32 v[128:129], v[0:1], v[128:129]
	v_pk_mul_f32 v[130:131], v[2:3], v[130:131]
	v_cvt_pk_bf16_f32 v128, v128, v129
	v_cvt_pk_bf16_f32 v129, v130, v131
	global_store_dwordx2 v151, v[128:129], s[2:3] offset:2048 sc1
	v_pk_mul_f32 v[132:133], v[132:133], v[170:171] op_sel_hi:[1,0]
	v_pk_mul_f32 v[134:135], v[134:135], v[170:171] op_sel_hi:[1,0]
	v_pk_mul_f32 v[132:133], v[4:5], v[132:133]
	v_pk_mul_f32 v[134:135], v[6:7], v[134:135]
	v_cvt_pk_bf16_f32 v132, v132, v133
	v_cvt_pk_bf16_f32 v133, v134, v135
	global_store_dwordx2 v151, v[132:133], s[2:3] offset:2560 sc1
	v_pk_mul_f32 v[136:137], v[136:137], v[170:171] op_sel_hi:[1,0]
	v_pk_mul_f32 v[138:139], v[138:139], v[170:171] op_sel_hi:[1,0]
	v_pk_mul_f32 v[136:137], v[8:9], v[136:137]
	v_pk_mul_f32 v[138:139], v[10:11], v[138:139]
	v_cvt_pk_bf16_f32 v136, v136, v137
	v_cvt_pk_bf16_f32 v137, v138, v139
	global_store_dwordx2 v151, v[136:137], s[2:3] offset:3072 sc1
	v_pk_mul_f32 v[140:141], v[140:141], v[170:171] op_sel_hi:[1,0]
	v_pk_mul_f32 v[142:143], v[142:143], v[170:171] op_sel_hi:[1,0]
	v_pk_mul_f32 v[140:141], v[12:13], v[140:141]
	v_pk_mul_f32 v[142:143], v[14:15], v[142:143]
	v_cvt_pk_bf16_f32 v140, v140, v141
	v_cvt_pk_bf16_f32 v141, v142, v143
	global_store_dwordx2 v151, v[140:141], s[2:3] offset:3584 sc1
	s_mov_b32 s41, s39
	s_cmp_lt_i32 s41, 0x8000
	s_cbranch_scc0 .Lrn_done
	s_branch .Lrn_step_A
.Lrn_done:
	s_branch .Lp0_norm_done
